# adaLN silu(c) loop unrolled: 16 loads issued up front, counted waits (was load-wait per iteration)
# baseline (speedup 1.0000x reference)
; __device__ __forceinline__ void phase_prologue(const Ctx& C) {
;     ...
;         for (int i = tid; i < BATCH * DM; i += 512) { const float v = cin[i]; sc[i] = v / (1.f + __expf(-v)); }
.LBB0_10:
	s_mov_b64 s[10:11], 0x1000
	global_load_dword v64, v[2:3], off
	global_load_dword v65, v[2:3], off offset:2048
	v_lshl_add_u64 v[2:3], v[2:3], 0, s[10:11]
	global_load_dword v66, v[2:3], off
	global_load_dword v67, v[2:3], off offset:2048
	v_lshl_add_u64 v[2:3], v[2:3], 0, s[10:11]
	global_load_dword v68, v[2:3], off
	global_load_dword v69, v[2:3], off offset:2048
	v_lshl_add_u64 v[2:3], v[2:3], 0, s[10:11]
	global_load_dword v70, v[2:3], off
	global_load_dword v71, v[2:3], off offset:2048
	v_lshl_add_u64 v[2:3], v[2:3], 0, s[10:11]
	global_load_dword v72, v[2:3], off
	global_load_dword v73, v[2:3], off offset:2048
	v_lshl_add_u64 v[2:3], v[2:3], 0, s[10:11]
	global_load_dword v74, v[2:3], off
	global_load_dword v75, v[2:3], off offset:2048
	v_lshl_add_u64 v[2:3], v[2:3], 0, s[10:11]
	global_load_dword v76, v[2:3], off
	global_load_dword v77, v[2:3], off offset:2048
	v_lshl_add_u64 v[2:3], v[2:3], 0, s[10:11]
	global_load_dword v78, v[2:3], off
	global_load_dword v79, v[2:3], off offset:2048
	s_mov_b64 s[10:11], 0x800
	s_waitcnt vmcnt(15)
	v_mul_f32_e32 v6, 0xbfb8aa3b, v64
	v_exp_f32_e32 v6, v6
	s_nop 0
	v_add_f32_e32 v6, 1.0, v6
	v_div_scale_f32 v7, s[14:15], v6, v6, v64
	v_rcp_f32_e32 v8, v7
	v_div_scale_f32 v9, vcc, v64, v6, v64
	v_fma_f32 v10, -v7, v8, 1.0
	v_fmac_f32_e32 v8, v10, v8
	v_mul_f32_e32 v10, v9, v8
	v_fma_f32 v11, -v7, v10, v9
	v_fmac_f32_e32 v10, v11, v8
	v_fma_f32 v7, -v7, v10, v9
	v_div_fmas_f32 v7, v7, v8, v10
	v_div_fixup_f32 v64, v7, v6, v64
	ds_write_b32 v4, v64 offset:0
	s_waitcnt vmcnt(14)
	v_mul_f32_e32 v6, 0xbfb8aa3b, v65
	v_exp_f32_e32 v6, v6
	s_nop 0
	v_add_f32_e32 v6, 1.0, v6
	v_div_scale_f32 v7, s[14:15], v6, v6, v65
	v_rcp_f32_e32 v8, v7
	v_div_scale_f32 v9, vcc, v65, v6, v65
	v_fma_f32 v10, -v7, v8, 1.0
	v_fmac_f32_e32 v8, v10, v8
	v_mul_f32_e32 v10, v9, v8
	v_fma_f32 v11, -v7, v10, v9
	v_fmac_f32_e32 v10, v11, v8
	v_fma_f32 v7, -v7, v10, v9
	v_div_fmas_f32 v7, v7, v8, v10
	v_div_fixup_f32 v65, v7, v6, v65
	ds_write_b32 v4, v65 offset:2048
	s_waitcnt vmcnt(13)
	v_mul_f32_e32 v6, 0xbfb8aa3b, v66
	v_exp_f32_e32 v6, v6
	s_nop 0
	v_add_f32_e32 v6, 1.0, v6
	v_div_scale_f32 v7, s[14:15], v6, v6, v66
	v_rcp_f32_e32 v8, v7
	v_div_scale_f32 v9, vcc, v66, v6, v66
	v_fma_f32 v10, -v7, v8, 1.0
	v_fmac_f32_e32 v8, v10, v8
	v_mul_f32_e32 v10, v9, v8
	v_fma_f32 v11, -v7, v10, v9
	v_fmac_f32_e32 v10, v11, v8
	v_fma_f32 v7, -v7, v10, v9
	v_div_fmas_f32 v7, v7, v8, v10
	v_div_fixup_f32 v66, v7, v6, v66
	ds_write_b32 v4, v66 offset:4096
	s_waitcnt vmcnt(12)
	v_mul_f32_e32 v6, 0xbfb8aa3b, v67
	v_exp_f32_e32 v6, v6
	s_nop 0
	v_add_f32_e32 v6, 1.0, v6
	v_div_scale_f32 v7, s[14:15], v6, v6, v67
	v_rcp_f32_e32 v8, v7
	v_div_scale_f32 v9, vcc, v67, v6, v67
	v_fma_f32 v10, -v7, v8, 1.0
	v_fmac_f32_e32 v8, v10, v8
	v_mul_f32_e32 v10, v9, v8
	v_fma_f32 v11, -v7, v10, v9
	v_fmac_f32_e32 v10, v11, v8
	v_fma_f32 v7, -v7, v10, v9
	v_div_fmas_f32 v7, v7, v8, v10
	v_div_fixup_f32 v67, v7, v6, v67
	ds_write_b32 v4, v67 offset:6144
	s_waitcnt vmcnt(11)
	v_mul_f32_e32 v6, 0xbfb8aa3b, v68
	v_exp_f32_e32 v6, v6
	s_nop 0
	v_add_f32_e32 v6, 1.0, v6
	v_div_scale_f32 v7, s[14:15], v6, v6, v68
	v_rcp_f32_e32 v8, v7
	v_div_scale_f32 v9, vcc, v68, v6, v68
	v_fma_f32 v10, -v7, v8, 1.0
	v_fmac_f32_e32 v8, v10, v8
	v_mul_f32_e32 v10, v9, v8
	v_fma_f32 v11, -v7, v10, v9
	v_fmac_f32_e32 v10, v11, v8
	v_fma_f32 v7, -v7, v10, v9
	v_div_fmas_f32 v7, v7, v8, v10
	v_div_fixup_f32 v68, v7, v6, v68
	ds_write_b32 v4, v68 offset:8192
	s_waitcnt vmcnt(10)
	v_mul_f32_e32 v6, 0xbfb8aa3b, v69
	v_exp_f32_e32 v6, v6
	s_nop 0
	v_add_f32_e32 v6, 1.0, v6
	v_div_scale_f32 v7, s[14:15], v6, v6, v69
	v_rcp_f32_e32 v8, v7
	v_div_scale_f32 v9, vcc, v69, v6, v69
	v_fma_f32 v10, -v7, v8, 1.0
	v_fmac_f32_e32 v8, v10, v8
	v_mul_f32_e32 v10, v9, v8
	v_fma_f32 v11, -v7, v10, v9
	v_fmac_f32_e32 v10, v11, v8
	v_fma_f32 v7, -v7, v10, v9
	v_div_fmas_f32 v7, v7, v8, v10
	v_div_fixup_f32 v69, v7, v6, v69
	ds_write_b32 v4, v69 offset:10240
	s_waitcnt vmcnt(9)
	v_mul_f32_e32 v6, 0xbfb8aa3b, v70
	v_exp_f32_e32 v6, v6
	s_nop 0
	v_add_f32_e32 v6, 1.0, v6
	v_div_scale_f32 v7, s[14:15], v6, v6, v70
	v_rcp_f32_e32 v8, v7
	v_div_scale_f32 v9, vcc, v70, v6, v70
	v_fma_f32 v10, -v7, v8, 1.0
	v_fmac_f32_e32 v8, v10, v8
	v_mul_f32_e32 v10, v9, v8
	v_fma_f32 v11, -v7, v10, v9
	v_fmac_f32_e32 v10, v11, v8
	v_fma_f32 v7, -v7, v10, v9
	v_div_fmas_f32 v7, v7, v8, v10
	v_div_fixup_f32 v70, v7, v6, v70
	ds_write_b32 v4, v70 offset:12288
	s_waitcnt vmcnt(8)
; __device__ __forceinline__ void phase_prologue(const Ctx& C) {
;     ...
;         for (int i = tid; i < BATCH * DM; i += 512) { const float v = cin[i]; sc[i] = v / (1.f + __expf(-v)); }
	v_mul_f32_e32 v6, 0xbfb8aa3b, v71
	v_exp_f32_e32 v6, v6
	s_nop 0
	v_add_f32_e32 v6, 1.0, v6
	v_div_scale_f32 v7, s[14:15], v6, v6, v71
	v_rcp_f32_e32 v8, v7
	v_div_scale_f32 v9, vcc, v71, v6, v71
	v_fma_f32 v10, -v7, v8, 1.0
	v_fmac_f32_e32 v8, v10, v8
	v_mul_f32_e32 v10, v9, v8
	v_fma_f32 v11, -v7, v10, v9
	v_fmac_f32_e32 v10, v11, v8
	v_fma_f32 v7, -v7, v10, v9
	v_div_fmas_f32 v7, v7, v8, v10
	v_div_fixup_f32 v71, v7, v6, v71
	ds_write_b32 v4, v71 offset:14336
	s_waitcnt vmcnt(7)
	v_mul_f32_e32 v6, 0xbfb8aa3b, v72
	v_exp_f32_e32 v6, v6
	s_nop 0
	v_add_f32_e32 v6, 1.0, v6
	v_div_scale_f32 v7, s[14:15], v6, v6, v72
	v_rcp_f32_e32 v8, v7
	v_div_scale_f32 v9, vcc, v72, v6, v72
	v_fma_f32 v10, -v7, v8, 1.0
	v_fmac_f32_e32 v8, v10, v8
	v_mul_f32_e32 v10, v9, v8
	v_fma_f32 v11, -v7, v10, v9
	v_fmac_f32_e32 v10, v11, v8
	v_fma_f32 v7, -v7, v10, v9
	v_div_fmas_f32 v7, v7, v8, v10
	v_div_fixup_f32 v72, v7, v6, v72
	ds_write_b32 v4, v72 offset:16384
	s_waitcnt vmcnt(6)
	v_mul_f32_e32 v6, 0xbfb8aa3b, v73
	v_exp_f32_e32 v6, v6
	s_nop 0
	v_add_f32_e32 v6, 1.0, v6
	v_div_scale_f32 v7, s[14:15], v6, v6, v73
	v_rcp_f32_e32 v8, v7
	v_div_scale_f32 v9, vcc, v73, v6, v73
	v_fma_f32 v10, -v7, v8, 1.0
	v_fmac_f32_e32 v8, v10, v8
	v_mul_f32_e32 v10, v9, v8
	v_fma_f32 v11, -v7, v10, v9
	v_fmac_f32_e32 v10, v11, v8
	v_fma_f32 v7, -v7, v10, v9
	v_div_fmas_f32 v7, v7, v8, v10
	v_div_fixup_f32 v73, v7, v6, v73
	ds_write_b32 v4, v73 offset:18432
	s_waitcnt vmcnt(5)
	v_mul_f32_e32 v6, 0xbfb8aa3b, v74
	v_exp_f32_e32 v6, v6
	s_nop 0
	v_add_f32_e32 v6, 1.0, v6
	v_div_scale_f32 v7, s[14:15], v6, v6, v74
	v_rcp_f32_e32 v8, v7
	v_div_scale_f32 v9, vcc, v74, v6, v74
	v_fma_f32 v10, -v7, v8, 1.0
	v_fmac_f32_e32 v8, v10, v8
	v_mul_f32_e32 v10, v9, v8
	v_fma_f32 v11, -v7, v10, v9
	v_fmac_f32_e32 v10, v11, v8
	v_fma_f32 v7, -v7, v10, v9
	v_div_fmas_f32 v7, v7, v8, v10
	v_div_fixup_f32 v74, v7, v6, v74
	ds_write_b32 v4, v74 offset:20480
	s_waitcnt vmcnt(4)
	v_mul_f32_e32 v6, 0xbfb8aa3b, v75
	v_exp_f32_e32 v6, v6
	s_nop 0
	v_add_f32_e32 v6, 1.0, v6
	v_div_scale_f32 v7, s[14:15], v6, v6, v75
	v_rcp_f32_e32 v8, v7
	v_div_scale_f32 v9, vcc, v75, v6, v75
	v_fma_f32 v10, -v7, v8, 1.0
	v_fmac_f32_e32 v8, v10, v8
	v_mul_f32_e32 v10, v9, v8
	v_fma_f32 v11, -v7, v10, v9
	v_fmac_f32_e32 v10, v11, v8
	v_fma_f32 v7, -v7, v10, v9
	v_div_fmas_f32 v7, v7, v8, v10
	v_div_fixup_f32 v75, v7, v6, v75
	ds_write_b32 v4, v75 offset:22528
	s_waitcnt vmcnt(3)
	v_mul_f32_e32 v6, 0xbfb8aa3b, v76
	v_exp_f32_e32 v6, v6
	s_nop 0
	v_add_f32_e32 v6, 1.0, v6
	v_div_scale_f32 v7, s[14:15], v6, v6, v76
	v_rcp_f32_e32 v8, v7
	v_div_scale_f32 v9, vcc, v76, v6, v76
	v_fma_f32 v10, -v7, v8, 1.0
	v_fmac_f32_e32 v8, v10, v8
	v_mul_f32_e32 v10, v9, v8
	v_fma_f32 v11, -v7, v10, v9
	v_fmac_f32_e32 v10, v11, v8
	v_fma_f32 v7, -v7, v10, v9
	v_div_fmas_f32 v7, v7, v8, v10
	v_div_fixup_f32 v76, v7, v6, v76
	ds_write_b32 v4, v76 offset:24576
	s_waitcnt vmcnt(2)
	v_mul_f32_e32 v6, 0xbfb8aa3b, v77
	v_exp_f32_e32 v6, v6
	s_nop 0
	v_add_f32_e32 v6, 1.0, v6
	v_div_scale_f32 v7, s[14:15], v6, v6, v77
	v_rcp_f32_e32 v8, v7
	v_div_scale_f32 v9, vcc, v77, v6, v77
	v_fma_f32 v10, -v7, v8, 1.0
	v_fmac_f32_e32 v8, v10, v8
	v_mul_f32_e32 v10, v9, v8
	v_fma_f32 v11, -v7, v10, v9
	v_fmac_f32_e32 v10, v11, v8
	v_fma_f32 v7, -v7, v10, v9
	v_div_fmas_f32 v7, v7, v8, v10
	v_div_fixup_f32 v77, v7, v6, v77
	ds_write_b32 v4, v77 offset:26624
	s_waitcnt vmcnt(1)
	v_mul_f32_e32 v6, 0xbfb8aa3b, v78
	v_exp_f32_e32 v6, v6
	s_nop 0
	v_add_f32_e32 v6, 1.0, v6
	v_div_scale_f32 v7, s[14:15], v6, v6, v78
	v_rcp_f32_e32 v8, v7
	v_div_scale_f32 v9, vcc, v78, v6, v78
	v_fma_f32 v10, -v7, v8, 1.0
	v_fmac_f32_e32 v8, v10, v8
	v_mul_f32_e32 v10, v9, v8
	v_fma_f32 v11, -v7, v10, v9
	v_fmac_f32_e32 v10, v11, v8
	v_fma_f32 v7, -v7, v10, v9
	v_div_fmas_f32 v7, v7, v8, v10
	v_div_fixup_f32 v78, v7, v6, v78
	ds_write_b32 v4, v78 offset:28672
	s_waitcnt vmcnt(0)
	v_mul_f32_e32 v6, 0xbfb8aa3b, v79
	v_exp_f32_e32 v6, v6
	s_nop 0
	v_add_f32_e32 v6, 1.0, v6
	v_div_scale_f32 v7, s[14:15], v6, v6, v79
	v_rcp_f32_e32 v8, v7
	v_div_scale_f32 v9, vcc, v79, v6, v79
	v_fma_f32 v10, -v7, v8, 1.0
	v_fmac_f32_e32 v8, v10, v8
	v_mul_f32_e32 v10, v9, v8
	v_fma_f32 v11, -v7, v10, v9
	v_fmac_f32_e32 v10, v11, v8
	v_fma_f32 v7, -v7, v10, v9
	v_div_fmas_f32 v7, v7, v8, v10
	v_div_fixup_f32 v79, v7, v6, v79
	ds_write_b32 v4, v79 offset:30720
